# banded mode-2 item prologue: first K tile loads issued with the Q/sink loads, wait vmcnt(8) (on top of v49)
# speedup vs baseline: 1.0171x; 1.0044x over previous
.LBB0_901:
	s_lshl_b32 s4, s47, 5
	s_and_b32 s50, s4, 0xfe0
	s_add_i32 s5, s50, 0x9f
	s_add_i32 s4, s50, 0xffffff80
	s_lshr_b32 s5, s5, 6
	s_bfe_u32 s48, s47, 0x40007
	s_ashr_i32 s49, s47, 11
	s_ashr_i32 s4, s4, 6
	s_add_i32 s5, s5, 1
	s_cmpk_lt_u32 s50, 0xf61
	s_cselect_b32 s51, s5, 64
	v_mov_b32_e32 v49, 0
	s_cmp_ge_i32 s4, s51
	v_mov_b32_e32 v48, 0
	v_mov_b32_e32 v47, 0
	v_mov_b32_e32 v46, 0
	v_mov_b32_e32 v45, 0
	v_mov_b32_e32 v44, 0
	v_mov_b32_e32 v43, 0
	v_mov_b32_e32 v42, 0
	v_mov_b32_e32 v41, 0
	v_mov_b32_e32 v40, 0
	v_mov_b32_e32 v39, 0
	v_mov_b32_e32 v38, 0
	v_mov_b32_e32 v37, 0
	v_mov_b32_e32 v36, 0
	v_mov_b32_e32 v35, 0
	v_mov_b32_e32 v34, 0
	v_mov_b32_e32 v65, 0
	v_mov_b32_e32 v64, 0
	v_mov_b32_e32 v63, 0
	v_mov_b32_e32 v62, 0
	v_mov_b32_e32 v61, 0
	v_mov_b32_e32 v60, 0
	v_mov_b32_e32 v59, 0
	v_mov_b32_e32 v58, 0
	v_mov_b32_e32 v57, 0
	v_mov_b32_e32 v56, 0
	v_mov_b32_e32 v55, 0
	v_mov_b32_e32 v54, 0
	v_mov_b32_e32 v53, 0
	v_mov_b32_e32 v52, 0
	v_mov_b32_e32 v51, 0
	v_mov_b32_e32 v50, 0
	v_mov_b32_e32 v214, v179
	s_cbranch_scc1 .LBB0_900
	s_and_b32 s5, s46, 0xfe0
	v_subrev_u32_e32 v212, s5, v211
	s_lshl_b32 s5, s49, 4
	s_or_b32 s6, s5, s48
	s_ashr_i32 s7, s6, 31
	s_lshl_b64 s[6:7], s[6:7], 12
	s_or_b32 s5, s6, s50
	v_mov_b32_e32 v1, s7
	v_or_b32_e32 v0, s5, v178
	s_lshr_b32 s5, s48, 2
	s_lshl_b32 s6, s49, 2
	v_lshlrev_b64 v[0:1], 7, v[0:1]
	s_or_b32 s6, s5, s6
	s_not_b32 s5, s48
	v_lshl_add_u64 v[0:1], v[180:181], 0, v[0:1]
	s_lshl_b32 s5, s5, 3
	global_load_dwordx4 v[98:101], v[0:1], off
	global_load_dwordx4 v[102:105], v[0:1], off offset:32
	global_load_dwordx4 v[106:109], v[0:1], off offset:64
	global_load_dwordx4 v[110:113], v[0:1], off offset:96
	v_cvt_f32_i32_e32 v0, s5
	s_ashr_i32 s7, s6, 31
	s_lshl_b64 s[6:7], s[6:7], 19
	v_lshl_add_u64 v[204:205], v[182:183], 0, s[6:7]
	v_mul_f32_e32 v1, 0x3d800000, v0
	v_cmp_gt_f32_e32 vcc, s8, v1
	v_lshl_add_u64 v[206:207], v[184:185], 0, s[6:7]
	s_and_b64 s[6:7], vcc, exec
	v_cndmask_b32_e32 v1, 0, v241, vcc
	v_fmac_f32_e32 v1, 0x3d800000, v0
	v_exp_f32_e32 v0, v1
	s_cselect_b32 s5, 0xffffffc0, 0
	s_mov_b64 s[6:7], s[58:59]
	s_mov_b32 s8, s65
	v_ldexp_f32 v0, v0, s5
	s_lshl_b32 s5, s48, 2
	v_mul_f32_e32 v4, 0x3fb8aa3b, v0
	v_mov_b32_e32 v0, s5
	s_mov_b32 s5, s64
	s_mov_b32 s9, s57
	v_readlane_b32 s52, v253, 2
	v_readlane_b32 s56, v253, 6
	v_readlane_b32 s57, v253, 7
	s_max_i32 s52, s4, 0
	s_lshl_b32 s16, s52, 13
	v_mov_b32_e32 v46, v33
	v_mov_b32_e32 v47, v33
	v_mov_b32_e32 v32, v33
	global_load_dword v0, v0, s[56:57]
	v_lshl_add_u64 v[6:7], v[204:205], 0, s[16:17]
	v_add_co_u32_e32 v8, vcc, s79, v6
	v_mov_b32_e32 v34, v33
	v_mov_b32_e32 v35, v33
	v_addc_co_u32_e32 v9, vcc, 0, v7, vcc
	global_load_dwordx4 v[114:117], v[8:9], off offset:3072
	global_load_dwordx4 v[118:121], v[8:9], off offset:2048
	global_load_dwordx4 v[122:125], v[8:9], off offset:1024
	global_load_dwordx4 v[126:129], v[8:9], off
	global_load_dwordx4 v[130:133], v[6:7], off offset:3072
	global_load_dwordx4 v[134:137], v[6:7], off offset:2048
	global_load_dwordx4 v[138:141], v[6:7], off offset:1024
	global_load_dwordx4 v[142:145], v[6:7], off
	v_mov_b32_e32 v36, v33
	v_mov_b32_e32 v37, v33
	v_mov_b32_e32 v38, v33
	v_mov_b32_e32 v39, v33
	v_mov_b32_e32 v40, v33
	v_mov_b32_e32 v41, v33
	v_mov_b32_e32 v42, v33
	v_mov_b32_e32 v43, v33
	v_mov_b32_e32 v44, v33
	v_mov_b32_e32 v45, v33
	v_mov_b64_e32 v[64:65], v[46:47]
	v_readlane_b32 s53, v253, 3
	v_readlane_b32 s54, v253, 4
	v_readlane_b32 s55, v253, 5
	v_readlane_b32 s58, v253, 8
	v_readlane_b32 s59, v253, 9
	v_readlane_b32 s60, v253, 10
	v_readlane_b32 s61, v253, 11
	v_readlane_b32 s62, v253, 12
	v_readlane_b32 s63, v253, 13
	v_readlane_b32 s64, v253, 14
	v_readlane_b32 s65, v253, 15
	v_readlane_b32 s66, v253, 16
	v_readlane_b32 s67, v253, 17
	v_readfirstlane_b32 s38, v4
	v_mov_b64_e32 v[62:63], v[44:45]
	v_mov_b64_e32 v[60:61], v[42:43]
	v_mov_b64_e32 v[58:59], v[40:41]
	v_mov_b64_e32 v[56:57], v[38:39]
	v_mov_b64_e32 v[54:55], v[36:37]
	v_mov_b64_e32 v[52:53], v[34:35]
	v_mov_b64_e32 v[50:51], v[32:33]
	v_mov_b64_e32 v[48:49], v[46:47]
	s_mov_b32 s65, s8
	s_mov_b32 s64, s5
	s_mov_b64 s[58:59], s[6:7]
	s_mov_b32 s57, s9
	s_add_i32 s53, s50, 0x42
	s_add_i32 s54, s50, 0xffffff9e
	s_mov_b32 s39, s38
	s_mov_b32 s55, s38
	s_mov_b32 s60, s38
	s_mov_b32 s61, s38
	s_mov_b32 s62, s38
	s_mov_b32 s63, s38
	s_mov_b32 s66, s38
	s_mov_b32 s67, s38
	s_mov_b32 s69, s38
	s_mov_b32 s70, s38
	s_mov_b32 s71, s38
	s_mov_b32 s80, s38
	s_mov_b32 s81, s38
	s_mov_b32 s82, s38
	s_mov_b32 s83, s38
	s_mov_b32 s84, s38
	s_mov_b32 s85, s38
	s_mov_b32 s86, s38
	s_mov_b32 s87, s38
	s_mov_b32 s88, s38
	s_mov_b32 s89, s38
	s_mov_b32 s93, s38
	s_mov_b32 s94, s38
	s_mov_b32 s95, s38
	s_mov_b32 s96, s38
	s_mov_b32 s97, s38
	s_mov_b32 s4, s38
	s_mov_b32 s5, s38
	s_mov_b32 s6, s38
	s_mov_b32 s7, s38
	s_mov_b32 s8, s38
	s_lshl_b32 s9, s52, 6
	s_mov_b64 s[40:41], s[16:17]
	v_mov_b64_e32 v[46:47], v[44:45]
	v_mov_b64_e32 v[44:45], v[42:43]
	v_mov_b64_e32 v[42:43], v[40:41]
	v_mov_b64_e32 v[40:41], v[38:39]
	v_mov_b64_e32 v[38:39], v[36:37]
	s_waitcnt vmcnt(8)
	v_mul_f32_e32 v213, 0x3fb8aa3b, v0
	v_mov_b64_e32 v[36:37], v[34:35]
	v_mov_b64_e32 v[34:35], v[32:33]
	v_mov_b32_e32 v214, v179
	s_branch .LBB0_904
